# grouped-query attention tile loop: same packed-f32 softmax row sums and exp2 arguments as the differential-attention loop
# baseline (speedup 1.0000x reference)
.LBB0_1106:
	ds_read_b128 v[64:67], v189 offset:49152
	ds_read_b128 v[68:71], v189 offset:57344
	ds_read_b128 v[232:235], v198 offset:49152
	ds_read_b128 v[236:239], v198 offset:57344
	s_waitcnt lgkmcnt(3)
	v_mfma_f32_32x32x16_bf16 v[80:95], v[64:67], v[112:115], 0
	v_add_f32_e32 v160, v161, v205
	v_add_f32_e32 v160, v210, v160
	v_pk_add_f32 v[202:203], v[162:163], v[208:209]
	v_add_f32_e32 v160, v167, v160
	s_waitcnt lgkmcnt(2)
	v_mfma_f32_32x32x16_bf16 v[64:79], v[68:71], v[112:115], 0
	v_exp_f32_e32 v158, v158
	v_pk_add_f32 v[202:203], v[202:203], v[168:169]
	v_exp_f32_e32 v159, v159
	v_pk_add_f32 v[202:203], v[202:203], v[170:171]
	s_waitcnt lgkmcnt(1)
	v_mfma_f32_32x32x16_bf16 v[80:95], v[232:235], v[108:111], v[80:95]
	v_exp_f32_e32 v156, v156
	v_pk_add_f32 v[202:203], v[202:203], v[172:173]
	v_exp_f32_e32 v157, v157
	v_pk_add_f32 v[202:203], v[202:203], v[174:175]
	v_exp_f32_e32 v152, v152
	v_exp_f32_e32 v153, v153
	s_waitcnt lgkmcnt(0)
	v_mfma_f32_32x32x16_bf16 v[64:79], v[236:239], v[108:111], v[64:79]
	ds_read_b128 v[232:235], v197 offset:49152
	ds_read_b128 v[236:239], v197 offset:57344
	v_pk_add_f32 v[202:203], v[202:203], v[158:159]
	v_exp_f32_e32 v148, v148
	v_exp_f32_e32 v149, v149
	v_pk_add_f32 v[202:203], v[202:203], v[156:157]
	v_exp_f32_e32 v146, v146
	s_waitcnt lgkmcnt(1)
	v_mfma_f32_32x32x16_bf16 v[80:95], v[232:235], v[120:123], v[80:95]
	v_exp_f32_e32 v147, v147
	v_pk_add_f32 v[202:203], v[202:203], v[152:153]
	v_exp_f32_e32 v154, v154
	v_exp_f32_e32 v155, v155
	v_pk_add_f32 v[202:203], v[202:203], v[148:149]
	s_waitcnt lgkmcnt(0)
	v_mfma_f32_32x32x16_bf16 v[64:79], v[236:239], v[120:123], v[64:79]
	ds_read_b128 v[232:235], v195 offset:49152
	ds_read_b128 v[236:239], v195 offset:57344
	v_exp_f32_e32 v150, v150
	v_exp_f32_e32 v151, v151
	v_pk_add_f32 v[202:203], v[202:203], v[146:147]
	v_exp_f32_e32 v144, v144
	s_waitcnt lgkmcnt(1)
	v_mfma_f32_32x32x16_bf16 v[80:95], v[232:235], v[124:127], v[80:95]
	v_exp_f32_e32 v145, v145
	v_pk_add_f32 v[202:203], v[202:203], v[154:155]
	v_pk_add_f32 v[202:203], v[202:203], v[150:151]
	v_pk_add_f32 v[202:203], v[202:203], v[144:145]
	v_add_f32_e32 v160, v202, v160
	v_add_f32_e32 v202, v203, v160
	v_mov_b32_e32 v203, v202
	s_waitcnt lgkmcnt(0)
	v_mfma_f32_32x32x16_bf16 v[64:79], v[236:239], v[124:127], v[64:79]
	ds_read_b128 v[232:235], v194 offset:49152
	ds_read_b128 v[236:239], v194 offset:57344
	v_cvt_pk_bf16_f32 v160, v161, v162
	v_cvt_pk_bf16_f32 v162, v209, v210
	v_cvt_pk_bf16_f32 v204, v167, v169
	v_cvt_pk_bf16_f32 v206, v168, v170
	v_permlane32_swap_b32_e32 v202, v203
	s_waitcnt lgkmcnt(1)
	v_mfma_f32_32x32x16_bf16 v[80:95], v[232:235], v[116:119], v[80:95]
	v_cvt_pk_bf16_f32 v161, v163, v205
	v_cvt_pk_bf16_f32 v163, v175, v208
	v_permlane32_swap_b32_e32 v160, v162
	v_cvt_pk_bf16_f32 v205, v171, v173
	v_cvt_pk_bf16_f32 v207, v172, v174
	v_permlane32_swap_b32_e32 v204, v206
	s_waitcnt lgkmcnt(0)
	v_mfma_f32_32x32x16_bf16 v[64:79], v[236:239], v[116:119], v[64:79]
	ds_read_b128 v[232:235], v196 offset:49152
	ds_read_b128 v[236:239], v196 offset:57344
	v_cvt_pk_bf16_f32 v168, v158, v159
	v_cvt_pk_bf16_f32 v169, v156, v157
	v_cvt_pk_bf16_f32 v170, v152, v153
	v_cvt_pk_bf16_f32 v171, v148, v149
	v_cvt_pk_bf16_f32 v172, v146, v147
	v_cvt_pk_bf16_f32 v173, v154, v155
	s_waitcnt lgkmcnt(1)
	v_mfma_f32_32x32x16_bf16 v[80:95], v[232:235], v[104:107], v[80:95]
	v_cvt_pk_bf16_f32 v174, v150, v151
	v_cvt_pk_bf16_f32 v175, v144, v145
	v_permlane32_swap_b32_e32 v161, v163
	v_permlane32_swap_b32_e32 v205, v207
	v_permlane32_swap_b32_e32 v168, v170
	s_waitcnt lgkmcnt(0)
	v_mfma_f32_32x32x16_bf16 v[64:79], v[236:239], v[104:107], v[64:79]
	ds_read_b128 v[232:235], v200 offset:49152
	ds_read_b128 v[236:239], v200 offset:57344
	v_permlane32_swap_b32_e32 v169, v171
	v_permlane32_swap_b32_e32 v172, v174
	v_permlane32_swap_b32_e32 v173, v175
	s_waitcnt lgkmcnt(1)
	v_mfma_f32_32x32x16_bf16 v[80:95], v[232:235], v[100:103], v[80:95]
	s_waitcnt lgkmcnt(0)
	v_mfma_f32_32x32x16_bf16 v[64:79], v[236:239], v[100:103], v[64:79]
	ds_read_b128 v[232:235], v199 offset:49152
	ds_read_b128 v[236:239], v199 offset:57344
	s_waitcnt lgkmcnt(1)
	v_mfma_f32_32x32x16_bf16 v[80:95], v[232:235], v[96:99], v[80:95]
	s_waitcnt lgkmcnt(0)
	v_mfma_f32_32x32x16_bf16 v[64:79], v[236:239], v[96:99], v[64:79]
	s_mov_b32 s4, 0xfff40000
	v_add_co_u32_e32 v148, vcc, s4, v180
	s_mov_b32 s4, 0xfff80000
	s_nop 0
	v_addc_co_u32_e32 v149, vcc, -1, v181, vcc
	v_add_co_u32_e32 v152, vcc, s4, v180
	s_nop 1
	v_addc_co_u32_e32 v153, vcc, -1, v181, vcc
	global_load_dwordx4 v[144:147], v[148:149], off
	s_nop 0
	global_load_dwordx4 v[148:151], v[148:149], off offset:-512
	s_nop 0
	global_load_dwordx4 v[156:159], v[152:153], off
	s_nop 0
	global_load_dwordx4 v[152:155], v[152:153], off offset:-512
	ds_read_b64_tr_b16 v[208:209], v188 offset:0
	ds_read_b64_tr_b16 v[210:211], v188 offset:0x800
	ds_read_b64_tr_b16 v[232:233], v188 offset:0x1000
	ds_read_b64_tr_b16 v[234:235], v188 offset:0x1800
	ds_read_b64_tr_b16 v[236:237], v188 offset:0x2000
	ds_read_b64_tr_b16 v[238:239], v188 offset:0x2800
	ds_read_b64_tr_b16 v[240:241], v188 offset:0x3000
	ds_read_b64_tr_b16 v[242:243], v188 offset:0x3800
	s_waitcnt lgkmcnt(0)
	s_nop 0
	v_mfma_f32_32x32x16_bf16 v[0:15], v[160:163], v[208:211], v[0:15]
	ds_read_b64_tr_b16 v[208:209], v188 offset:0x200
	ds_read_b64_tr_b16 v[210:211], v188 offset:0xa00
	v_mfma_f32_32x32x16_bf16 v[0:15], v[204:207], v[232:235], v[0:15]
	ds_read_b64_tr_b16 v[232:233], v188 offset:0x1200
	ds_read_b64_tr_b16 v[234:235], v188 offset:0x1a00
	v_mfma_f32_32x32x16_bf16 v[0:15], v[168:171], v[236:239], v[0:15]
	ds_read_b64_tr_b16 v[236:237], v188 offset:0x2200
	ds_read_b64_tr_b16 v[238:239], v188 offset:0x2a00
	v_mfma_f32_32x32x16_bf16 v[0:15], v[172:175], v[240:243], v[0:15]
	ds_read_b64_tr_b16 v[240:241], v188 offset:0x3200
	ds_read_b64_tr_b16 v[242:243], v188 offset:0x3a00
	s_waitcnt lgkmcnt(0)
	v_mfma_f32_32x32x16_bf16 v[48:63], v[160:163], v[208:211], v[48:63]
	ds_read_b64_tr_b16 v[208:209], v188 offset:0x400
	ds_read_b64_tr_b16 v[210:211], v188 offset:0xc00
	v_mfma_f32_32x32x16_bf16 v[48:63], v[204:207], v[232:235], v[48:63]
	ds_read_b64_tr_b16 v[232:233], v188 offset:0x1400
	ds_read_b64_tr_b16 v[234:235], v188 offset:0x1c00
	v_mfma_f32_32x32x16_bf16 v[48:63], v[168:171], v[236:239], v[48:63]
	ds_read_b64_tr_b16 v[236:237], v188 offset:0x2400
	ds_read_b64_tr_b16 v[238:239], v188 offset:0x2c00
	v_mfma_f32_32x32x16_bf16 v[48:63], v[172:175], v[240:243], v[48:63]
	ds_read_b64_tr_b16 v[240:241], v188 offset:0x3400
	ds_read_b64_tr_b16 v[242:243], v188 offset:0x3c00
	s_waitcnt lgkmcnt(0)
	v_mfma_f32_32x32x16_bf16 v[32:47], v[160:163], v[208:211], v[32:47]
	ds_read_b64_tr_b16 v[208:209], v188 offset:0x600
	ds_read_b64_tr_b16 v[210:211], v188 offset:0xe00
	v_mfma_f32_32x32x16_bf16 v[32:47], v[204:207], v[232:235], v[32:47]
	ds_read_b64_tr_b16 v[232:233], v188 offset:0x1600
	ds_read_b64_tr_b16 v[234:235], v188 offset:0x1e00
	v_mfma_f32_32x32x16_bf16 v[32:47], v[168:171], v[236:239], v[32:47]
	ds_read_b64_tr_b16 v[236:237], v188 offset:0x2600
	ds_read_b64_tr_b16 v[238:239], v188 offset:0x2e00
	v_mfma_f32_32x32x16_bf16 v[32:47], v[172:175], v[240:243], v[32:47]
	ds_read_b64_tr_b16 v[240:241], v188 offset:0x3600
	ds_read_b64_tr_b16 v[242:243], v188 offset:0x3e00
	s_waitcnt lgkmcnt(0)
	v_mfma_f32_32x32x16_bf16 v[16:31], v[160:163], v[208:211], v[16:31]
	v_max_f32_e32 v160, v81, v81
	v_max_f32_e32 v161, v80, v80
	v_max_f32_e32 v160, v161, v160
	v_max3_f32 v160, v160, v82, v83
	v_max3_f32 v160, v160, v84, v85
	v_max3_f32 v160, v160, v86, v87
	v_max3_f32 v160, v160, v88, v89
	v_max3_f32 v160, v160, v90, v91
	v_max3_f32 v160, v160, v92, v93
	v_mfma_f32_32x32x16_bf16 v[16:31], v[204:207], v[232:235], v[16:31]
	v_max3_f32 v160, v160, v94, v95
	v_max3_f32 v160, v160, v64, v65
	v_max3_f32 v160, v160, v66, v67
	v_max3_f32 v160, v160, v68, v69
	v_max3_f32 v160, v160, v70, v71
	v_max3_f32 v160, v160, v72, v73
	v_max3_f32 v160, v160, v74, v75
	v_max3_f32 v160, v160, v76, v77
	v_mfma_f32_32x32x16_bf16 v[16:31], v[168:171], v[236:239], v[16:31]
	v_max3_f32 v160, v160, v78, v79
	v_mov_b32_e32 v161, v160
	s_nop 1
	v_permlane32_swap_b32_e32 v160, v161
	v_max_f32_e32 v161, v161, v161
	v_max_f32_e32 v160, v160, v160
	v_max_f32_e32 v160, v160, v161
	v_sub_f32_e32 v161, v160, v166
	v_cmp_ge_f32_e32 vcc, s42, v161
	v_max_f32_e32 v161, v166, v166
	v_max_f32_e32 v160, v161, v160
	v_mfma_f32_32x32x16_bf16 v[16:31], v[172:175], v[240:243], v[16:31]
	v_sub_f32_e32 v161, v166, v160
	v_mul_f32_e32 v161, 0x3e0293ee, v161
	v_exp_f32_e32 v161, v161
	s_cmp_eq_u64 vcc, exec
	s_cselect_b64 s[4:5], -1, 0
	s_barrier
	s_waitcnt vmcnt(4)
	v_cndmask_b32_e64 v204, v161, 1.0, s[4:5]
	v_cmp_gt_f32_e32 vcc, 1.0, v204
	s_waitcnt vmcnt(4)
	ds_write_b128 v192, v[136:139]
	ds_write_b128 v193, v[140:143]
	ds_write_b128 v190, v[128:131] offset:32768
	ds_write_b128 v191, v[132:135] offset:32768
	s_cbranch_vccz .LBB0_1110
	s_and_saveexec_b64 s[8:9], s[6:7]
	ds_write_b32 v179, v204 offset:128
	s_or_b64 exec, exec, s[8:9]
	s_waitcnt lgkmcnt(0)
	v_add_u32_e32 v161, v176, v178
	ds_read_b128 v[162:165], v161 offset:224
	ds_read_b128 v[168:171], v161 offset:192
	ds_read_b128 v[172:175], v161 offset:160
	ds_read_b128 v[206:209], v161 offset:128
	s_waitcnt lgkmcnt(3)
	v_pk_mul_f32 v[12:13], v[12:13], v[162:163]
	s_waitcnt lgkmcnt(2)
	v_pk_mul_f32 v[8:9], v[8:9], v[168:169]
	s_waitcnt lgkmcnt(1)
	v_pk_mul_f32 v[4:5], v[4:5], v[172:173]
	v_pk_mul_f32 v[14:15], v[14:15], v[164:165]
	v_pk_mul_f32 v[10:11], v[10:11], v[170:171]
	v_pk_mul_f32 v[6:7], v[6:7], v[174:175]
	s_waitcnt lgkmcnt(0)
	v_pk_mul_f32 v[2:3], v[2:3], v[208:209]
	v_pk_mul_f32 v[0:1], v[0:1], v[206:207]
	v_pk_mul_f32 v[60:61], v[60:61], v[162:163]
	v_pk_mul_f32 v[56:57], v[56:57], v[168:169]
	v_pk_mul_f32 v[52:53], v[52:53], v[172:173]
	v_pk_mul_f32 v[62:63], v[62:63], v[164:165]
	v_pk_mul_f32 v[58:59], v[58:59], v[170:171]
	v_pk_mul_f32 v[54:55], v[54:55], v[174:175]
	v_pk_mul_f32 v[50:51], v[50:51], v[208:209]
	v_pk_mul_f32 v[48:49], v[48:49], v[206:207]
	v_pk_mul_f32 v[44:45], v[44:45], v[162:163]
	v_pk_mul_f32 v[40:41], v[40:41], v[168:169]
	v_pk_mul_f32 v[36:37], v[36:37], v[172:173]
	v_pk_mul_f32 v[46:47], v[46:47], v[164:165]
	v_pk_mul_f32 v[42:43], v[42:43], v[170:171]
	v_pk_mul_f32 v[38:39], v[38:39], v[174:175]
	v_pk_mul_f32 v[34:35], v[34:35], v[208:209]
	v_pk_mul_f32 v[32:33], v[32:33], v[206:207]
	v_pk_mul_f32 v[28:29], v[28:29], v[162:163]
	v_pk_mul_f32 v[24:25], v[24:25], v[168:169]
	v_pk_mul_f32 v[20:21], v[20:21], v[172:173]
	v_pk_mul_f32 v[30:31], v[30:31], v[164:165]
	v_pk_mul_f32 v[26:27], v[26:27], v[170:171]
	v_pk_mul_f32 v[22:23], v[22:23], v[174:175]
	v_pk_mul_f32 v[18:19], v[18:19], v[208:209]
	v_pk_mul_f32 v[16:17], v[16:17], v[206:207]
.LBB0_1110:
	v_cndmask_b32_e64 v205, v160, v166, s[4:5]
	v_mul_f32_e32 v206, 0xbe0293ee, v205
	v_pk_fma_f32 v[80:81], v[80:81], s[52:53], v[206:207] op_sel_hi:[1,0,0]
	v_pk_fma_f32 v[82:83], v[82:83], s[52:53], v[206:207] op_sel_hi:[1,0,0]
	v_pk_fma_f32 v[84:85], v[84:85], s[52:53], v[206:207] op_sel_hi:[1,0,0]
	v_pk_fma_f32 v[86:87], v[86:87], s[52:53], v[206:207] op_sel_hi:[1,0,0]
	v_pk_fma_f32 v[88:89], v[88:89], s[52:53], v[206:207] op_sel_hi:[1,0,0]
	v_pk_fma_f32 v[90:91], v[90:91], s[52:53], v[206:207] op_sel_hi:[1,0,0]
	v_pk_fma_f32 v[92:93], v[92:93], s[52:53], v[206:207] op_sel_hi:[1,0,0]
	v_pk_fma_f32 v[94:95], v[94:95], s[52:53], v[206:207] op_sel_hi:[1,0,0]
	v_exp_f32_e32 v160, v80
	v_exp_f32_e32 v161, v81
	v_exp_f32_e32 v162, v82
	v_exp_f32_e32 v173, v83
	v_exp_f32_e32 v174, v84
	v_exp_f32_e32 v175, v85
	v_exp_f32_e32 v163, v86
	v_exp_f32_e32 v172, v87
	v_exp_f32_e32 v164, v88
	v_exp_f32_e32 v165, v89
	v_exp_f32_e32 v170, v90
	v_exp_f32_e32 v171, v91
	v_exp_f32_e32 v166, v92
	v_exp_f32_e32 v167, v93
	v_exp_f32_e32 v168, v94
	v_exp_f32_e32 v169, v95
	v_fmamk_f32 v232, v64, 0x3e0293ee, v206
	v_fmamk_f32 v233, v65, 0x3e0293ee, v206
	v_fmamk_f32 v234, v66, 0x3e0293ee, v206
	v_fmamk_f32 v235, v67, 0x3e0293ee, v206
	v_fmamk_f32 v236, v68, 0x3e0293ee, v206
	v_fmamk_f32 v208, v69, 0x3e0293ee, v206
	v_fmamk_f32 v209, v70, 0x3e0293ee, v206
	v_fmamk_f32 v210, v71, 0x3e0293ee, v206
	v_fmamk_f32 v211, v72, 0x3e0293ee, v206
	v_fmamk_f32 v212, v73, 0x3e0293ee, v206
	v_fmamk_f32 v213, v74, 0x3e0293ee, v206
	v_fmamk_f32 v231, v75, 0x3e0293ee, v206
	v_fmamk_f32 v207, v76, 0x3e0293ee, v206
	v_fmamk_f32 v237, v77, 0x3e0293ee, v206
	v_fmamk_f32 v238, v78, 0x3e0293ee, v206
	v_fmac_f32_e32 v206, 0x3e0293ee, v79
	s_waitcnt lgkmcnt(0)
	s_barrier
	ds_read_b128 v[64:67], v189 offset:32768
	ds_read_b128 v[68:71], v189 offset:40960
	ds_read_b128 v[240:243], v198 offset:32768
	ds_read_b128 v[244:247], v198 offset:40960
	v_exp_f32_e32 v220, v232
	v_exp_f32_e32 v232, v206
	s_waitcnt lgkmcnt(3)
	v_mfma_f32_32x32x16_bf16 v[80:95], v[64:67], v[112:115], 0
	v_pk_add_f32 v[248:249], v[160:161], v[174:175]
	v_pk_add_f32 v[248:249], v[248:249], v[162:163]
	s_waitcnt lgkmcnt(2)
	v_mfma_f32_32x32x16_bf16 v[64:79], v[68:71], v[112:115], 0
	v_pk_add_f32 v[248:249], v[248:249], v[172:173]
	v_pk_add_f32 v[248:249], v[248:249], v[164:165]
	v_pk_add_f32 v[248:249], v[248:249], v[170:171]
	v_exp_f32_e32 v221, v233
	s_waitcnt lgkmcnt(1)
	v_mfma_f32_32x32x16_bf16 v[80:95], v[240:243], v[108:111], v[80:95]
	v_pk_add_f32 v[248:249], v[248:249], v[166:167]
	v_exp_f32_e32 v222, v234
	v_exp_f32_e32 v223, v235
	v_pk_add_f32 v[248:249], v[248:249], v[168:169]
	v_exp_f32_e32 v224, v236
	s_waitcnt lgkmcnt(0)
	v_mfma_f32_32x32x16_bf16 v[64:79], v[244:247], v[108:111], v[64:79]
	ds_read_b128 v[240:243], v197 offset:32768
	ds_read_b128 v[244:247], v197 offset:40960
	v_exp_f32_e32 v208, v208
	v_pk_add_f32 v[248:249], v[248:249], v[220:221]
	v_exp_f32_e32 v209, v209
	v_exp_f32_e32 v210, v210
	v_pk_add_f32 v[248:249], v[248:249], v[222:223]
	s_waitcnt lgkmcnt(1)
	v_mfma_f32_32x32x16_bf16 v[80:95], v[240:243], v[120:123], v[80:95]
	v_exp_f32_e32 v211, v211
	v_exp_f32_e32 v212, v212
	v_exp_f32_e32 v213, v213
	v_pk_add_f32 v[248:249], v[248:249], v[208:209]
	v_exp_f32_e32 v225, v231
	s_waitcnt lgkmcnt(0)
	v_mfma_f32_32x32x16_bf16 v[64:79], v[244:247], v[120:123], v[64:79]
	ds_read_b128 v[240:243], v195 offset:32768
	ds_read_b128 v[244:247], v195 offset:40960
	v_exp_f32_e32 v228, v207
	v_pk_add_f32 v[248:249], v[248:249], v[210:211]
	v_exp_f32_e32 v229, v237
	v_exp_f32_e32 v231, v238
	s_waitcnt lgkmcnt(1)
	v_mfma_f32_32x32x16_bf16 v[80:95], v[240:243], v[124:127], v[80:95]
	v_pk_add_f32 v[248:249], v[248:249], v[212:213]
	v_pk_add_f32 v[248:249], v[248:249], v[224:225]
	v_pk_add_f32 v[248:249], v[248:249], v[228:229]
	v_add_f32_e32 v250, v231, v232
	v_add_f32_e32 v250, v248, v250
	v_add_f32_e32 v206, v249, v250
	v_mov_b32_e32 v207, v206
	s_waitcnt lgkmcnt(0)
	v_mfma_f32_32x32x16_bf16 v[64:79], v[244:247], v[124:127], v[64:79]
	ds_read_b128 v[240:243], v194 offset:32768
	ds_read_b128 v[244:247], v194 offset:40960
	v_cvt_pk_bf16_f32 v160, v160, v161
	v_cvt_pk_bf16_f32 v161, v162, v173
	v_cvt_pk_bf16_f32 v162, v174, v175
	v_cvt_pk_bf16_f32 v163, v163, v172
	v_cvt_pk_bf16_f32 v164, v164, v165
	v_cvt_pk_bf16_f32 v165, v170, v171
	s_waitcnt lgkmcnt(1)
	v_mfma_f32_32x32x16_bf16 v[80:95], v[240:243], v[116:119], v[80:95]
	v_cvt_pk_bf16_f32 v166, v166, v167
	v_cvt_pk_bf16_f32 v167, v168, v169
	v_cvt_pk_bf16_f32 v168, v220, v221
	v_cvt_pk_bf16_f32 v169, v222, v223
	v_cvt_pk_bf16_f32 v170, v224, v208
	v_cvt_pk_bf16_f32 v171, v209, v210
	v_cvt_pk_bf16_f32 v172, v211, v212
	s_waitcnt lgkmcnt(0)
	v_mfma_f32_32x32x16_bf16 v[64:79], v[244:247], v[116:119], v[64:79]
	ds_read_b128 v[240:243], v196 offset:32768
	ds_read_b128 v[244:247], v196 offset:40960
	v_cvt_pk_bf16_f32 v173, v213, v225
	v_cvt_pk_bf16_f32 v174, v228, v229
	v_cvt_pk_bf16_f32 v175, v231, v232
	v_permlane32_swap_b32_e32 v206, v207
	v_permlane32_swap_b32_e32 v160, v162
	s_waitcnt lgkmcnt(1)
	v_mfma_f32_32x32x16_bf16 v[80:95], v[240:243], v[104:107], v[80:95]
	v_permlane32_swap_b32_e32 v161, v163
	v_permlane32_swap_b32_e32 v164, v166
	v_permlane32_swap_b32_e32 v165, v167
	v_permlane32_swap_b32_e32 v168, v170
	s_waitcnt lgkmcnt(0)
	v_mfma_f32_32x32x16_bf16 v[64:79], v[244:247], v[104:107], v[64:79]
	ds_read_b128 v[240:243], v200 offset:32768
	ds_read_b128 v[244:247], v200 offset:40960
	v_permlane32_swap_b32_e32 v169, v171
	v_permlane32_swap_b32_e32 v172, v174
	v_permlane32_swap_b32_e32 v173, v175
	s_waitcnt lgkmcnt(1)
	v_mfma_f32_32x32x16_bf16 v[80:95], v[240:243], v[100:103], v[80:95]
	s_waitcnt lgkmcnt(0)
	v_mfma_f32_32x32x16_bf16 v[64:79], v[244:247], v[100:103], v[64:79]
	ds_read_b128 v[240:243], v199 offset:32768
	ds_read_b128 v[244:247], v199 offset:40960
	s_waitcnt lgkmcnt(1)
	v_mfma_f32_32x32x16_bf16 v[80:95], v[240:243], v[96:99], v[80:95]
	s_waitcnt lgkmcnt(0)
	v_mfma_f32_32x32x16_bf16 v[64:79], v[244:247], v[96:99], v[64:79]
	s_add_i32 s26, s26, 2
	s_cmp_ge_u32 s26, s27
	s_cselect_b64 s[8:9], -1, 0
	s_and_b64 vcc, exec, s[8:9]
	s_cbranch_vccnz .LBB0_1112
	v_add_co_u32_e32 v128, vcc, 0xfffc0000, v180
	s_nop 1
	v_addc_co_u32_e32 v129, vcc, -1, v181, vcc
	global_load_dwordx4 v[136:139], v[128:129], off
	s_nop 0
	global_load_dwordx4 v[128:131], v[128:129], off offset:-512
	s_nop 0
	global_load_dwordx4 v[140:143], v[180:181], off
	global_load_dwordx4 v[132:135], v[180:181], off offset:-512

.LBB0_1116:
	v_cndmask_b32_e64 v166, v161, v205, s[4:5]
	v_mul_f32_e32 v144, 0xbe0293ee, v166
	v_pk_fma_f32 v[80:81], v[80:81], s[52:53], v[144:145] op_sel_hi:[1,0,0]
	v_pk_fma_f32 v[82:83], v[82:83], s[52:53], v[144:145] op_sel_hi:[1,0,0]
	v_pk_fma_f32 v[84:85], v[84:85], s[52:53], v[144:145] op_sel_hi:[1,0,0]
	v_pk_fma_f32 v[86:87], v[86:87], s[52:53], v[144:145] op_sel_hi:[1,0,0]
	v_pk_fma_f32 v[88:89], v[88:89], s[52:53], v[144:145] op_sel_hi:[1,0,0]
	v_pk_fma_f32 v[90:91], v[90:91], s[52:53], v[144:145] op_sel_hi:[1,0,0]
	v_pk_fma_f32 v[92:93], v[92:93], s[52:53], v[144:145] op_sel_hi:[1,0,0]
	v_pk_fma_f32 v[94:95], v[94:95], s[52:53], v[144:145] op_sel_hi:[1,0,0]
	v_exp_f32_e32 v161, v80
	v_exp_f32_e32 v162, v81
	v_exp_f32_e32 v163, v82
	v_exp_f32_e32 v205, v83
	v_exp_f32_e32 v209, v84
	v_exp_f32_e32 v210, v85
	v_exp_f32_e32 v175, v86
	v_exp_f32_e32 v208, v87
	v_exp_f32_e32 v167, v88
	v_exp_f32_e32 v169, v89
	v_exp_f32_e32 v171, v90
	v_exp_f32_e32 v173, v91
	v_exp_f32_e32 v168, v92
	v_exp_f32_e32 v170, v93
	v_exp_f32_e32 v172, v94
	v_exp_f32_e32 v174, v95
	v_pk_fma_f32 v[158:159], v[64:65], s[52:53], v[144:145] op_sel_hi:[1,0,0]
	v_add_f32_e32 v64, v202, v203
	v_fmac_f32_e32 v64, v201, v186
	v_add_f32_e32 v186, v206, v207
	v_pk_fma_f32 v[156:157], v[66:67], s[52:53], v[144:145] op_sel_hi:[1,0,0]
	v_pk_fma_f32 v[152:153], v[68:69], s[52:53], v[144:145] op_sel_hi:[1,0,0]
	v_pk_fma_f32 v[148:149], v[70:71], s[52:53], v[144:145] op_sel_hi:[1,0,0]
	v_pk_fma_f32 v[146:147], v[72:73], s[52:53], v[144:145] op_sel_hi:[1,0,0]
	v_pk_fma_f32 v[154:155], v[74:75], s[52:53], v[144:145] op_sel_hi:[1,0,0]
	v_pk_fma_f32 v[150:151], v[76:77], s[52:53], v[144:145] op_sel_hi:[1,0,0]
	v_pk_fma_f32 v[144:145], v[78:79], s[52:53], v[144:145] op_sel_hi:[1,0,0]
	v_fmac_f32_e32 v186, v64, v204
	v_lshl_add_u64 v[180:181], v[180:181], 0, s[0:1]
	s_and_b64 vcc, exec, s[8:9]
	s_waitcnt lgkmcnt(0)
	s_barrier
	s_cbranch_vccnz .LBB0_1118
	v_mov_b32_e32 v201, v160
	s_branch .LBB0_1106
